# DOWN (layer 1) epilogue: residual-row loads issued together with the per-column factor vectors; plus ctx attention prologue DMA and FFT stage-0 load hoist
# baseline (speedup 1.0000x reference)
.LBB0_1532:
	s_lshr_b32 s33, s19, 3
	s_cmp_lt_i32 s19, 64
	s_mulk_i32 s33, 0x1800
	s_cselect_b32 s50, s33, 0xc000
	s_ashr_i32 s51, s50, 31
	s_lshl_b32 s19, s19, 8
	s_add_i32 s19, s19, s10
	s_lshl_b64 s[48:49], s[50:51], 2
	s_add_u32 s33, s26, s48
	s_addc_u32 s49, s27, s49
	v_mov_b32_e32 v132, v0
	s_add_u32 s48, s33, 0x5000
	s_addc_u32 s49, s49, 0
	v_lshrrev_b32_e32 v133, 1, v132
	s_lshl_b32 s18, s18, 8
	v_and_or_b32 v133, v133, 24, s18
	v_or_b32_e32 v196, s11, v133
	s_add_i32 s18, s50, 0x1000
	v_lshlrev_b32_e32 v144, 2, v196
	v_add_lshl_u32 v152, v196, s18, 2
	v_and_or_b32 v156, v132, 15, s19
	global_load_dwordx4 v[132:135], v144, s[48:49] offset:16
	global_load_dwordx4 v[136:139], v144, s[48:49]
	global_load_dwordx4 v[214:217], v144, s[42:43] offset:16
	s_nop 0
	global_load_dwordx4 v[218:221], v144, s[42:43]
	s_nop 0
	global_load_dwordx4 v[222:225], v152, s[26:27] offset:16
	s_nop 0
	global_load_dwordx4 v[226:229], v152, s[26:27]
	v_lshlrev_b32_e32 v189, 1, v196
	v_lshlrev_b32_e32 v197, 11, v156
	v_add_u32_e32 v188, v189, v197
	global_load_dwordx4 v[204:207], v188, s[96:97] nt
	v_or_b32_e32 v198, 0x8000, v197
	v_or_b32_e32 v190, 0x10000, v197
	v_or_b32_e32 v191, 0x18000, v197
	v_add_u32_e32 v192, 0x40000, v197
	v_add_u32_e32 v193, 0x48000, v197
	v_add_u32_e32 v194, 0x50000, v197
	v_add_u32_e32 v195, 0x58000, v197
	s_and_b64 vcc, exec, s[38:39]
	v_add_u32_e32 v140, v189, v198
	global_load_dwordx4 v[164:167], v140, s[96:97] nt
	v_add_u32_e32 v140, v189, v190
	global_load_dwordx4 v[160:163], v140, s[96:97] nt
	v_add_u32_e32 v140, v189, v191
	global_load_dwordx4 v[156:159], v140, s[96:97] nt
	v_add_u32_e32 v140, v189, v192
	global_load_dwordx4 v[152:155], v140, s[96:97] nt
	v_add_u32_e32 v140, v189, v193
	global_load_dwordx4 v[148:151], v140, s[96:97] nt
	v_add_u32_e32 v140, v189, v194
	global_load_dwordx4 v[144:147], v140, s[96:97] nt
	v_add_u32_e32 v140, v189, v195
	global_load_dwordx4 v[140:143], v140, s[96:97] nt
	s_waitcnt vmcnt(7)
	v_pk_add_f32 v[228:229], v[228:229], 1.0 op_sel_hi:[1,0]
	s_nop 0
	v_pk_mul_f32 v[220:221], v[220:221], v[228:229]
	v_pk_add_f32 v[226:227], v[226:227], 1.0 op_sel_hi:[1,0]
	v_rcp_f32_e32 v182, v220
	v_rcp_f32_e32 v183, v221
	v_pk_add_f32 v[220:221], v[222:223], 1.0 op_sel_hi:[1,0]
	v_pk_mul_f32 v[218:219], v[218:219], v[226:227]
	v_pk_mul_f32 v[214:215], v[214:215], v[220:221]
	v_rcp_f32_e32 v178, v218
	v_rcp_f32_e32 v180, v214
	v_rcp_f32_e32 v179, v219
	v_pk_add_f32 v[218:219], v[224:225], 1.0 op_sel_hi:[1,0]
	v_pk_mul_f32 v[184:185], v[216:217], v[218:219]
	v_rcp_f32_e32 v181, v215
	v_rcp_f32_e32 v184, v184
	v_rcp_f32_e32 v185, v185
	v_lshlrev_b32_e32 v208, 16, v204
	v_and_b32_e32 v209, 0xffff0000, v204
	v_lshlrev_b32_e32 v204, 16, v205
	v_and_b32_e32 v205, 0xffff0000, v205
	v_lshlrev_b32_e32 v210, 16, v206
	v_and_b32_e32 v211, 0xffff0000, v206
	v_lshlrev_b32_e32 v206, 16, v207
	v_and_b32_e32 v207, 0xffff0000, v207
	v_pk_mul_f32 v[204:205], v[182:183], v[204:205]
	v_pk_mul_f32 v[208:209], v[178:179], v[208:209]
	v_pk_mul_f32 v[206:207], v[184:185], v[206:207]
	v_pk_mul_f32 v[210:211], v[180:181], v[210:211]
	v_pk_fma_f32 v[130:131], v[130:131], v[138:139], v[204:205]
	v_pk_fma_f32 v[128:129], v[128:129], v[136:137], v[208:209]
	v_pk_fma_f32 v[204:205], v[126:127], v[134:135], v[206:207]
	v_pk_fma_f32 v[206:207], v[124:125], v[132:133], v[210:211]
	v_mov_b32_e32 v126, v129
	v_mov_b32_e32 v127, v207
	v_mov_b32_e32 v124, v128
	v_mov_b32_e32 v125, v206
	v_pk_mul_f32 v[126:127], v[126:127], v[126:127]
	v_mov_b32_e32 v208, v131
	v_mov_b32_e32 v209, v205
	v_pk_fma_f32 v[124:125], v[124:125], v[124:125], v[126:127]
	v_mov_b32_e32 v126, v130
	v_mov_b32_e32 v127, v204
	v_pk_mul_f32 v[208:209], v[208:209], v[208:209]
	s_nop 0
	v_pk_fma_f32 v[126:127], v[126:127], v[126:127], v[208:209]
	s_nop 0
	v_pk_add_f32 v[124:125], v[124:125], v[126:127]
	v_cvt_pk_bf16_f32 v126, v128, v129
	v_add_f32_e32 v124, v124, v125
	v_cvt_pk_bf16_f32 v127, v130, v131
	v_cvt_pk_bf16_f32 v128, v206, v207
	v_cvt_pk_bf16_f32 v129, v204, v205
	global_store_dwordx4 v188, v[126:129], s[96:97]
	v_add_u32_e32 v125, 0x8000, v188
	s_waitcnt vmcnt(7)
	v_lshlrev_b32_e32 v130, 16, v166
	v_lshlrev_b32_e32 v126, 16, v164
	v_and_b32_e32 v127, 0xffff0000, v164
	v_lshlrev_b32_e32 v128, 16, v165
	v_and_b32_e32 v129, 0xffff0000, v165
	v_and_b32_e32 v131, 0xffff0000, v166
	v_lshlrev_b32_e32 v164, 16, v167
	v_and_b32_e32 v165, 0xffff0000, v167
	v_pk_mul_f32 v[128:129], v[182:183], v[128:129]
	v_pk_mul_f32 v[126:127], v[178:179], v[126:127]
	v_pk_mul_f32 v[130:131], v[180:181], v[130:131]
	v_pk_mul_f32 v[164:165], v[184:185], v[164:165]
	v_pk_fma_f32 v[122:123], v[122:123], v[138:139], v[128:129]
	v_pk_fma_f32 v[120:121], v[120:121], v[136:137], v[126:127]
	v_pk_fma_f32 v[128:129], v[116:117], v[132:133], v[130:131]
	v_pk_fma_f32 v[126:127], v[118:119], v[134:135], v[164:165]
	v_mov_b32_e32 v118, v121
	v_mov_b32_e32 v119, v129
	v_mov_b32_e32 v116, v120
	v_mov_b32_e32 v117, v128
	v_pk_mul_f32 v[118:119], v[118:119], v[118:119]
	v_mov_b32_e32 v130, v123
	v_mov_b32_e32 v131, v127
	v_pk_fma_f32 v[116:117], v[116:117], v[116:117], v[118:119]
	v_mov_b32_e32 v118, v122
	v_mov_b32_e32 v119, v126
	v_pk_mul_f32 v[130:131], v[130:131], v[130:131]
	s_nop 0
	v_pk_fma_f32 v[118:119], v[118:119], v[118:119], v[130:131]
	s_nop 0
	v_pk_add_f32 v[116:117], v[116:117], v[118:119]
	v_cvt_pk_bf16_f32 v118, v120, v121
	v_add_f32_e32 v116, v116, v117
	v_cvt_pk_bf16_f32 v119, v122, v123
	v_cvt_pk_bf16_f32 v120, v128, v129
	v_cvt_pk_bf16_f32 v121, v126, v127
	global_store_dwordx4 v125, v[118:121], s[96:97]
	s_waitcnt vmcnt(7)
	v_lshlrev_b32_e32 v122, 16, v162
	v_and_b32_e32 v123, 0xffff0000, v162
	v_lshlrev_b32_e32 v118, 16, v160
	v_and_b32_e32 v119, 0xffff0000, v160
	v_lshlrev_b32_e32 v120, 16, v161
	v_and_b32_e32 v121, 0xffff0000, v161
	v_lshlrev_b32_e32 v126, 16, v163
	v_and_b32_e32 v127, 0xffff0000, v163
	v_pk_mul_f32 v[120:121], v[182:183], v[120:121]
	v_pk_mul_f32 v[118:119], v[178:179], v[118:119]
	v_pk_mul_f32 v[122:123], v[180:181], v[122:123]
	v_pk_mul_f32 v[126:127], v[184:185], v[126:127]
	v_pk_fma_f32 v[114:115], v[114:115], v[138:139], v[120:121]
	v_pk_fma_f32 v[112:113], v[112:113], v[136:137], v[118:119]
	v_pk_fma_f32 v[120:121], v[108:109], v[132:133], v[122:123]
	v_pk_fma_f32 v[118:119], v[110:111], v[134:135], v[126:127]
	v_mov_b32_e32 v110, v113
	v_mov_b32_e32 v111, v121
	v_mov_b32_e32 v108, v112
	v_mov_b32_e32 v109, v120
	v_pk_mul_f32 v[110:111], v[110:111], v[110:111]
	v_mov_b32_e32 v122, v115
	v_mov_b32_e32 v123, v119
	v_pk_fma_f32 v[108:109], v[108:109], v[108:109], v[110:111]
	v_mov_b32_e32 v110, v114
	v_mov_b32_e32 v111, v118
	v_pk_mul_f32 v[122:123], v[122:123], v[122:123]
	v_add_u32_e32 v117, 0x10000, v188
	v_pk_fma_f32 v[110:111], v[110:111], v[110:111], v[122:123]
	s_nop 0
	v_pk_add_f32 v[108:109], v[108:109], v[110:111]
	v_cvt_pk_bf16_f32 v110, v112, v113
	v_add_f32_e32 v108, v108, v109
	v_cvt_pk_bf16_f32 v111, v114, v115
	v_cvt_pk_bf16_f32 v112, v120, v121
	v_cvt_pk_bf16_f32 v113, v118, v119
	global_store_dwordx4 v117, v[110:113], s[96:97]
	s_waitcnt vmcnt(7)
	v_lshlrev_b32_e32 v114, 16, v158
	v_and_b32_e32 v115, 0xffff0000, v158
	v_lshlrev_b32_e32 v110, 16, v156
	v_and_b32_e32 v111, 0xffff0000, v156
	v_lshlrev_b32_e32 v112, 16, v157
	v_and_b32_e32 v113, 0xffff0000, v157
	v_lshlrev_b32_e32 v118, 16, v159
	v_and_b32_e32 v119, 0xffff0000, v159
	v_pk_mul_f32 v[112:113], v[182:183], v[112:113]
	v_pk_mul_f32 v[110:111], v[178:179], v[110:111]
	v_pk_mul_f32 v[118:119], v[184:185], v[118:119]
	v_pk_mul_f32 v[114:115], v[180:181], v[114:115]
	v_pk_fma_f32 v[106:107], v[106:107], v[138:139], v[112:113]
	v_pk_fma_f32 v[110:111], v[104:105], v[136:137], v[110:111]
	v_pk_fma_f32 v[112:113], v[102:103], v[134:135], v[118:119]
	v_pk_fma_f32 v[102:103], v[100:101], v[132:133], v[114:115]
	v_mov_b32_e32 v104, v111
	v_mov_b32_e32 v105, v103
	v_mov_b32_e32 v100, v110
	v_mov_b32_e32 v101, v102
	v_pk_mul_f32 v[104:105], v[104:105], v[104:105]
	v_mov_b32_e32 v114, v107
	v_mov_b32_e32 v115, v113
	v_pk_fma_f32 v[100:101], v[100:101], v[100:101], v[104:105]
	v_mov_b32_e32 v104, v106
	v_mov_b32_e32 v105, v112
	v_pk_mul_f32 v[114:115], v[114:115], v[114:115]
	v_add_u32_e32 v109, 0x18000, v188
	v_pk_fma_f32 v[104:105], v[104:105], v[104:105], v[114:115]
	v_cvt_pk_bf16_f32 v102, v102, v103
	v_pk_add_f32 v[100:101], v[100:101], v[104:105]
	v_cvt_pk_bf16_f32 v103, v112, v113
	v_add_f32_e32 v104, v100, v101
	v_cvt_pk_bf16_f32 v100, v110, v111
	v_cvt_pk_bf16_f32 v101, v106, v107
	global_store_dwordx4 v109, v[100:103], s[96:97]
	s_waitcnt vmcnt(7)
	v_lshlrev_b32_e32 v106, 16, v154
	v_and_b32_e32 v107, 0xffff0000, v154
	v_lshlrev_b32_e32 v100, 16, v152
	v_and_b32_e32 v101, 0xffff0000, v152
	v_lshlrev_b32_e32 v110, 16, v155
	v_and_b32_e32 v111, 0xffff0000, v155
	v_lshlrev_b32_e32 v102, 16, v153
	v_and_b32_e32 v103, 0xffff0000, v153
	v_pk_mul_f32 v[100:101], v[178:179], v[100:101]
	v_pk_mul_f32 v[110:111], v[184:185], v[110:111]
	v_pk_mul_f32 v[106:107], v[180:181], v[106:107]
	v_pk_mul_f32 v[102:103], v[182:183], v[102:103]
	v_pk_fma_f32 v[94:95], v[94:95], v[136:137], v[100:101]
	v_pk_fma_f32 v[100:101], v[92:93], v[134:135], v[110:111]
	v_pk_fma_f32 v[92:93], v[90:91], v[132:133], v[106:107]
	v_pk_fma_f32 v[96:97], v[96:97], v[138:139], v[102:103]
	v_mov_b32_e32 v102, v95
	v_mov_b32_e32 v103, v93
	v_mov_b32_e32 v90, v94
	v_mov_b32_e32 v91, v92
	v_pk_mul_f32 v[102:103], v[102:103], v[102:103]
	v_mov_b32_e32 v106, v97
	v_mov_b32_e32 v107, v101
	v_pk_fma_f32 v[90:91], v[90:91], v[90:91], v[102:103]
	v_mov_b32_e32 v102, v96
	v_mov_b32_e32 v103, v100
	v_pk_mul_f32 v[106:107], v[106:107], v[106:107]
	v_add_u32_e32 v105, 0x40000, v188
	v_pk_fma_f32 v[102:103], v[102:103], v[102:103], v[106:107]
	v_cvt_pk_bf16_f32 v92, v92, v93
	v_pk_add_f32 v[90:91], v[90:91], v[102:103]
	v_cvt_pk_bf16_f32 v93, v100, v101
	v_add_f32_e32 v103, v90, v91
	v_cvt_pk_bf16_f32 v90, v94, v95
	v_cvt_pk_bf16_f32 v91, v96, v97
	global_store_dwordx4 v105, v[90:93], s[96:97]
	s_waitcnt vmcnt(7)
	v_lshlrev_b32_e32 v94, 16, v150
	v_and_b32_e32 v95, 0xffff0000, v150
	v_lshlrev_b32_e32 v90, 16, v148
	v_and_b32_e32 v91, 0xffff0000, v148
	v_lshlrev_b32_e32 v96, 16, v151
	v_and_b32_e32 v97, 0xffff0000, v151
	v_lshlrev_b32_e32 v92, 16, v149
	v_and_b32_e32 v93, 0xffff0000, v149
	v_pk_mul_f32 v[90:91], v[178:179], v[90:91]
	v_pk_mul_f32 v[96:97], v[184:185], v[96:97]
	v_pk_mul_f32 v[94:95], v[180:181], v[94:95]
	v_pk_mul_f32 v[92:93], v[182:183], v[92:93]
	v_pk_fma_f32 v[86:87], v[86:87], v[136:137], v[90:91]
	v_pk_fma_f32 v[90:91], v[84:85], v[134:135], v[96:97]
	v_pk_fma_f32 v[84:85], v[82:83], v[132:133], v[94:95]
	v_pk_fma_f32 v[88:89], v[88:89], v[138:139], v[92:93]
	v_mov_b32_e32 v92, v87
	v_mov_b32_e32 v93, v85
	v_mov_b32_e32 v82, v86
	v_mov_b32_e32 v83, v84
	v_pk_mul_f32 v[92:93], v[92:93], v[92:93]
	v_mov_b32_e32 v94, v89
	v_mov_b32_e32 v95, v91
	v_pk_fma_f32 v[82:83], v[82:83], v[82:83], v[92:93]
	v_mov_b32_e32 v92, v88
	v_mov_b32_e32 v93, v90
	v_pk_mul_f32 v[94:95], v[94:95], v[94:95]
	v_add_u32_e32 v100, 0x48000, v188
	v_pk_fma_f32 v[92:93], v[92:93], v[92:93], v[94:95]
	v_cvt_pk_bf16_f32 v84, v84, v85
	v_pk_add_f32 v[82:83], v[82:83], v[92:93]
	v_cvt_pk_bf16_f32 v85, v90, v91
	v_add_f32_e32 v102, v82, v83
	v_cvt_pk_bf16_f32 v82, v86, v87
	v_cvt_pk_bf16_f32 v83, v88, v89
	global_store_dwordx4 v100, v[82:85], s[96:97]
	s_waitcnt vmcnt(7)
	v_lshlrev_b32_e32 v86, 16, v146
	v_and_b32_e32 v87, 0xffff0000, v146
	v_lshlrev_b32_e32 v82, 16, v144
	v_and_b32_e32 v83, 0xffff0000, v144
	v_lshlrev_b32_e32 v88, 16, v147
	v_and_b32_e32 v89, 0xffff0000, v147
	v_lshlrev_b32_e32 v84, 16, v145
	v_and_b32_e32 v85, 0xffff0000, v145
	v_pk_mul_f32 v[82:83], v[178:179], v[82:83]
	v_pk_mul_f32 v[88:89], v[184:185], v[88:89]
	v_pk_mul_f32 v[86:87], v[180:181], v[86:87]
	v_pk_mul_f32 v[84:85], v[182:183], v[84:85]
	v_pk_fma_f32 v[78:79], v[78:79], v[136:137], v[82:83]
	v_pk_fma_f32 v[82:83], v[76:77], v[134:135], v[88:89]
	v_pk_fma_f32 v[76:77], v[74:75], v[132:133], v[86:87]
	v_pk_fma_f32 v[80:81], v[80:81], v[138:139], v[84:85]
	v_mov_b32_e32 v84, v79
	v_mov_b32_e32 v85, v77
	v_mov_b32_e32 v74, v78
	v_mov_b32_e32 v75, v76
	v_pk_mul_f32 v[84:85], v[84:85], v[84:85]
	v_mov_b32_e32 v86, v81
	v_mov_b32_e32 v87, v83
	v_pk_fma_f32 v[74:75], v[74:75], v[74:75], v[84:85]
	v_mov_b32_e32 v84, v80
	v_mov_b32_e32 v85, v82
	v_pk_mul_f32 v[86:87], v[86:87], v[86:87]
	v_add_u32_e32 v90, 0x50000, v188
	v_pk_fma_f32 v[84:85], v[84:85], v[84:85], v[86:87]
	v_cvt_pk_bf16_f32 v76, v76, v77
	v_pk_add_f32 v[74:75], v[74:75], v[84:85]
	v_cvt_pk_bf16_f32 v77, v82, v83
	v_add_f32_e32 v101, v74, v75
	v_cvt_pk_bf16_f32 v74, v78, v79
	v_cvt_pk_bf16_f32 v75, v80, v81
	global_store_dwordx4 v90, v[74:77], s[96:97]
	s_waitcnt vmcnt(7)
	v_lshlrev_b32_e32 v78, 16, v142
	v_and_b32_e32 v79, 0xffff0000, v142
	v_lshlrev_b32_e32 v74, 16, v140
	v_and_b32_e32 v75, 0xffff0000, v140
	v_lshlrev_b32_e32 v80, 16, v143
	v_and_b32_e32 v81, 0xffff0000, v143
	v_lshlrev_b32_e32 v76, 16, v141
	v_and_b32_e32 v77, 0xffff0000, v141
	v_pk_mul_f32 v[74:75], v[178:179], v[74:75]
	v_pk_mul_f32 v[80:81], v[184:185], v[80:81]
	v_pk_mul_f32 v[78:79], v[180:181], v[78:79]
	v_pk_mul_f32 v[76:77], v[182:183], v[76:77]
	v_pk_fma_f32 v[70:71], v[70:71], v[136:137], v[74:75]
	v_pk_fma_f32 v[74:75], v[68:69], v[134:135], v[80:81]
	v_pk_fma_f32 v[68:69], v[66:67], v[132:133], v[78:79]
	v_pk_fma_f32 v[72:73], v[72:73], v[138:139], v[76:77]
	v_mov_b32_e32 v76, v71
	v_mov_b32_e32 v77, v69
	v_mov_b32_e32 v66, v70
	v_mov_b32_e32 v67, v68
	v_pk_mul_f32 v[76:77], v[76:77], v[76:77]
	v_mov_b32_e32 v78, v73
	v_mov_b32_e32 v79, v75
	v_pk_fma_f32 v[66:67], v[66:67], v[66:67], v[76:77]
	v_mov_b32_e32 v76, v72
	v_mov_b32_e32 v77, v74
	v_pk_mul_f32 v[78:79], v[78:79], v[78:79]
	v_add_u32_e32 v82, 0x58000, v188
	v_pk_fma_f32 v[76:77], v[76:77], v[76:77], v[78:79]
	v_cvt_pk_bf16_f32 v68, v68, v69
	v_pk_add_f32 v[66:67], v[66:67], v[76:77]
	v_cvt_pk_bf16_f32 v69, v74, v75
	v_add_f32_e32 v100, v66, v67
	v_cvt_pk_bf16_f32 v66, v70, v71
	v_cvt_pk_bf16_f32 v67, v72, v73
	global_store_dwordx4 v82, v[66:69], s[96:97]
	v_or_b32_e32 v82, 0x80, v196
	v_lshlrev_b32_e32 v78, 2, v82
	v_add_lshl_u32 v86, v82, s18, 2
	global_load_dwordx4 v[66:69], v78, s[48:49] offset:16
	global_load_dwordx4 v[70:73], v78, s[48:49]
	global_load_dwordx4 v[214:217], v78, s[42:43] offset:16
	s_nop 0
	global_load_dwordx4 v[218:221], v78, s[42:43]
	s_nop 0
	global_load_dwordx4 v[222:225], v86, s[26:27] offset:16
	s_nop 0
	global_load_dwordx4 v[226:229], v86, s[26:27]
	v_or_b32_e32 v105, 0x100, v188
	s_mov_b64 s[48:49], -1
	v_or_b32_e32 v74, 0x100, v189
	v_add_u32_e32 v75, v74, v197
	global_load_dwordx4 v[110:113], v75, s[96:97] nt
	v_add_u32_e32 v75, v74, v198
	global_load_dwordx4 v[118:121], v75, s[96:97] nt
	v_add_u32_e32 v75, v74, v190
	global_load_dwordx4 v[126:129], v75, s[96:97] nt
	v_add_u32_e32 v75, v74, v191
	global_load_dwordx4 v[130:133], v75, s[96:97] nt
	v_add_u32_e32 v75, v74, v192
	global_load_dwordx4 v[86:89], v75, s[96:97] nt
	v_add_u32_e32 v75, v74, v193
	global_load_dwordx4 v[82:85], v75, s[96:97] nt
	v_add_u32_e32 v75, v74, v194
	global_load_dwordx4 v[78:81], v75, s[96:97] nt
	v_add_u32_e32 v74, v74, v195
	global_load_dwordx4 v[74:77], v74, s[96:97] nt
	s_waitcnt vmcnt(8)
	v_pk_add_f32 v[228:229], v[228:229], 1.0 op_sel_hi:[1,0]
	s_nop 0
	v_pk_mul_f32 v[220:221], v[220:221], v[228:229]
	v_pk_add_f32 v[226:227], v[226:227], 1.0 op_sel_hi:[1,0]
	v_rcp_f32_e32 v94, v220
	v_rcp_f32_e32 v95, v221
	v_pk_add_f32 v[220:221], v[222:223], 1.0 op_sel_hi:[1,0]
	v_pk_mul_f32 v[218:219], v[218:219], v[226:227]
	v_pk_mul_f32 v[214:215], v[214:215], v[220:221]
	v_rcp_f32_e32 v90, v218
	v_rcp_f32_e32 v92, v214
	v_rcp_f32_e32 v93, v215
	v_rcp_f32_e32 v91, v219
	v_pk_add_f32 v[218:219], v[224:225], 1.0 op_sel_hi:[1,0]
	v_pk_mul_f32 v[96:97], v[216:217], v[218:219]
	v_rcp_f32_e32 v96, v96
	v_rcp_f32_e32 v97, v97
	s_waitcnt vmcnt(7)
	v_lshlrev_b32_e32 v106, 16, v110
	v_and_b32_e32 v107, 0xffff0000, v110
	v_lshlrev_b32_e32 v114, 16, v112
	v_and_b32_e32 v115, 0xffff0000, v112
	v_lshlrev_b32_e32 v112, 16, v113
	v_and_b32_e32 v113, 0xffff0000, v113
	v_lshlrev_b32_e32 v110, 16, v111
	v_and_b32_e32 v111, 0xffff0000, v111
	v_pk_mul_f32 v[106:107], v[90:91], v[106:107]
	v_pk_mul_f32 v[112:113], v[96:97], v[112:113]
	v_pk_mul_f32 v[114:115], v[92:93], v[114:115]
	v_pk_mul_f32 v[110:111], v[94:95], v[110:111]
	v_pk_fma_f32 v[62:63], v[62:63], v[70:71], v[106:107]
	v_pk_fma_f32 v[106:107], v[60:61], v[68:69], v[112:113]
	v_pk_fma_f32 v[60:61], v[58:59], v[66:67], v[114:115]
	v_pk_fma_f32 v[64:65], v[64:65], v[72:73], v[110:111]
	v_mov_b32_e32 v110, v63
	v_mov_b32_e32 v111, v61
	v_mov_b32_e32 v58, v62
	v_mov_b32_e32 v59, v60
	v_pk_mul_f32 v[110:111], v[110:111], v[110:111]
	v_mov_b32_e32 v112, v65
	v_mov_b32_e32 v113, v107
	v_pk_fma_f32 v[58:59], v[58:59], v[58:59], v[110:111]
	v_mov_b32_e32 v110, v64
	v_mov_b32_e32 v111, v106
	v_pk_mul_f32 v[112:113], v[112:113], v[112:113]
	v_cvt_pk_bf16_f32 v60, v60, v61
	v_pk_fma_f32 v[110:111], v[110:111], v[110:111], v[112:113]
	v_cvt_pk_bf16_f32 v61, v106, v107
	v_pk_add_f32 v[58:59], v[58:59], v[110:111]
	s_nop 0
	v_add_f32_e32 v58, v58, v59
	v_add_f32_e32 v58, v124, v58
	v_cvt_pk_bf16_f32 v59, v64, v65
	v_cvt_pk_bf16_f32 v58, v62, v63
	global_store_dwordx4 v105, v[58:61], s[96:97]
	s_waitcnt vmcnt(7)
	v_lshlrev_b32_e32 v62, 16, v120
	v_and_b32_e32 v63, 0xffff0000, v120
	v_lshlrev_b32_e32 v58, 16, v118
	v_and_b32_e32 v59, 0xffff0000, v118
	v_lshlrev_b32_e32 v64, 16, v121
	v_and_b32_e32 v65, 0xffff0000, v121
	v_lshlrev_b32_e32 v60, 16, v119
	v_and_b32_e32 v61, 0xffff0000, v119
	v_pk_mul_f32 v[58:59], v[90:91], v[58:59]
	v_pk_mul_f32 v[64:65], v[96:97], v[64:65]
	v_pk_mul_f32 v[62:63], v[92:93], v[62:63]
	v_pk_mul_f32 v[60:61], v[94:95], v[60:61]
	v_pk_fma_f32 v[54:55], v[54:55], v[70:71], v[58:59]
	v_pk_fma_f32 v[58:59], v[52:53], v[68:69], v[64:65]
	v_pk_fma_f32 v[52:53], v[50:51], v[66:67], v[62:63]
	v_pk_fma_f32 v[56:57], v[56:57], v[72:73], v[60:61]
	v_mov_b32_e32 v60, v55
	v_mov_b32_e32 v61, v53
	v_mov_b32_e32 v50, v54
	v_mov_b32_e32 v51, v52
	v_pk_mul_f32 v[60:61], v[60:61], v[60:61]
	v_mov_b32_e32 v62, v57
	v_mov_b32_e32 v63, v59
	v_pk_fma_f32 v[50:51], v[50:51], v[50:51], v[60:61]
	v_mov_b32_e32 v60, v56
	v_mov_b32_e32 v61, v58
	v_pk_mul_f32 v[62:63], v[62:63], v[62:63]
	v_add_u32_e32 v105, 0x8100, v188
	v_pk_fma_f32 v[60:61], v[60:61], v[60:61], v[62:63]
	v_cvt_pk_bf16_f32 v52, v52, v53
	v_pk_add_f32 v[50:51], v[50:51], v[60:61]
	v_cvt_pk_bf16_f32 v53, v58, v59
	v_add_f32_e32 v50, v50, v51
	v_add_f32_e32 v50, v116, v50
	v_cvt_pk_bf16_f32 v51, v56, v57
	v_cvt_pk_bf16_f32 v50, v54, v55
	global_store_dwordx4 v105, v[50:53], s[96:97]
	s_waitcnt vmcnt(7)
	v_lshlrev_b32_e32 v54, 16, v128
	v_and_b32_e32 v55, 0xffff0000, v128
	v_lshlrev_b32_e32 v50, 16, v126
	v_and_b32_e32 v51, 0xffff0000, v126
	v_lshlrev_b32_e32 v56, 16, v129
	v_and_b32_e32 v57, 0xffff0000, v129
	v_lshlrev_b32_e32 v52, 16, v127
	v_and_b32_e32 v53, 0xffff0000, v127
	v_pk_mul_f32 v[50:51], v[90:91], v[50:51]
	v_pk_mul_f32 v[56:57], v[96:97], v[56:57]
	v_pk_mul_f32 v[54:55], v[92:93], v[54:55]
	v_pk_mul_f32 v[52:53], v[94:95], v[52:53]
	v_pk_fma_f32 v[46:47], v[46:47], v[70:71], v[50:51]
	v_pk_fma_f32 v[50:51], v[44:45], v[68:69], v[56:57]
	v_pk_fma_f32 v[44:45], v[42:43], v[66:67], v[54:55]
	v_pk_fma_f32 v[48:49], v[48:49], v[72:73], v[52:53]
	v_mov_b32_e32 v52, v47
	v_mov_b32_e32 v53, v45
	v_mov_b32_e32 v42, v46
	v_mov_b32_e32 v43, v44
	v_pk_mul_f32 v[52:53], v[52:53], v[52:53]
	v_mov_b32_e32 v54, v49
	v_mov_b32_e32 v55, v51
	v_pk_fma_f32 v[42:43], v[42:43], v[42:43], v[52:53]
	v_mov_b32_e32 v52, v48
	v_mov_b32_e32 v53, v50
	v_pk_mul_f32 v[54:55], v[54:55], v[54:55]
	v_add_u32_e32 v58, 0x10100, v188
	v_pk_fma_f32 v[52:53], v[52:53], v[52:53], v[54:55]
	v_cvt_pk_bf16_f32 v44, v44, v45
	v_pk_add_f32 v[42:43], v[42:43], v[52:53]
	v_cvt_pk_bf16_f32 v45, v50, v51
	v_add_f32_e32 v42, v42, v43
	v_add_f32_e32 v42, v108, v42
	v_cvt_pk_bf16_f32 v43, v48, v49
	v_cvt_pk_bf16_f32 v42, v46, v47
	global_store_dwordx4 v58, v[42:45], s[96:97]
	s_waitcnt vmcnt(7)
	v_lshlrev_b32_e32 v46, 16, v132
	v_and_b32_e32 v47, 0xffff0000, v132
	v_lshlrev_b32_e32 v42, 16, v130
	v_and_b32_e32 v43, 0xffff0000, v130
	v_lshlrev_b32_e32 v48, 16, v133
	v_and_b32_e32 v49, 0xffff0000, v133
	v_lshlrev_b32_e32 v44, 16, v131
	v_and_b32_e32 v45, 0xffff0000, v131
	v_pk_mul_f32 v[42:43], v[90:91], v[42:43]
	v_pk_mul_f32 v[48:49], v[96:97], v[48:49]
	v_pk_mul_f32 v[46:47], v[92:93], v[46:47]
	v_pk_mul_f32 v[44:45], v[94:95], v[44:45]
	v_pk_fma_f32 v[38:39], v[38:39], v[70:71], v[42:43]
	v_pk_fma_f32 v[42:43], v[36:37], v[68:69], v[48:49]
	v_pk_fma_f32 v[36:37], v[34:35], v[66:67], v[46:47]
	v_pk_fma_f32 v[40:41], v[40:41], v[72:73], v[44:45]
	v_mov_b32_e32 v44, v39
	v_mov_b32_e32 v45, v37
	v_mov_b32_e32 v34, v38
	v_mov_b32_e32 v35, v36
	v_pk_mul_f32 v[44:45], v[44:45], v[44:45]
	v_mov_b32_e32 v46, v41
	v_mov_b32_e32 v47, v43
	v_pk_fma_f32 v[34:35], v[34:35], v[34:35], v[44:45]
	v_mov_b32_e32 v44, v40
	v_mov_b32_e32 v45, v42
	v_pk_mul_f32 v[46:47], v[46:47], v[46:47]
	v_add_u32_e32 v50, 0x18100, v188
	v_pk_fma_f32 v[44:45], v[44:45], v[44:45], v[46:47]
	v_cvt_pk_bf16_f32 v36, v36, v37
	v_pk_add_f32 v[34:35], v[34:35], v[44:45]
	v_cvt_pk_bf16_f32 v37, v42, v43
	v_add_f32_e32 v34, v34, v35
	v_add_f32_e32 v34, v104, v34
	v_cvt_pk_bf16_f32 v35, v40, v41
	v_cvt_pk_bf16_f32 v34, v38, v39
	global_store_dwordx4 v50, v[34:37], s[96:97]
	s_waitcnt vmcnt(7)
	v_lshlrev_b32_e32 v38, 16, v88
	v_and_b32_e32 v39, 0xffff0000, v88
	v_lshlrev_b32_e32 v34, 16, v86
	v_and_b32_e32 v35, 0xffff0000, v86
	v_lshlrev_b32_e32 v40, 16, v89
	v_and_b32_e32 v41, 0xffff0000, v89
	v_lshlrev_b32_e32 v36, 16, v87
	v_and_b32_e32 v37, 0xffff0000, v87
	v_pk_mul_f32 v[34:35], v[90:91], v[34:35]
	v_pk_mul_f32 v[40:41], v[96:97], v[40:41]
	v_pk_mul_f32 v[38:39], v[92:93], v[38:39]
	v_pk_mul_f32 v[36:37], v[94:95], v[36:37]
	v_pk_fma_f32 v[30:31], v[30:31], v[70:71], v[34:35]
	v_pk_fma_f32 v[34:35], v[28:29], v[68:69], v[40:41]
	v_pk_fma_f32 v[28:29], v[26:27], v[66:67], v[38:39]
	v_pk_fma_f32 v[32:33], v[32:33], v[72:73], v[36:37]
	v_mov_b32_e32 v36, v31
	v_mov_b32_e32 v37, v29
	v_mov_b32_e32 v26, v30
	v_mov_b32_e32 v27, v28
	v_pk_mul_f32 v[36:37], v[36:37], v[36:37]
	v_mov_b32_e32 v38, v33
	v_mov_b32_e32 v39, v35
	v_pk_fma_f32 v[26:27], v[26:27], v[26:27], v[36:37]
	v_mov_b32_e32 v36, v32
	v_mov_b32_e32 v37, v34
	v_pk_mul_f32 v[38:39], v[38:39], v[38:39]
	v_add_u32_e32 v42, 0x40100, v188
	v_pk_fma_f32 v[36:37], v[36:37], v[36:37], v[38:39]
	v_cvt_pk_bf16_f32 v28, v28, v29
	v_pk_add_f32 v[26:27], v[26:27], v[36:37]
	v_cvt_pk_bf16_f32 v29, v34, v35
	v_add_f32_e32 v26, v26, v27
	v_add_f32_e32 v26, v103, v26
	v_cvt_pk_bf16_f32 v27, v32, v33
	v_cvt_pk_bf16_f32 v26, v30, v31
	global_store_dwordx4 v42, v[26:29], s[96:97]
	s_waitcnt vmcnt(7)
	v_lshlrev_b32_e32 v30, 16, v84
	v_and_b32_e32 v31, 0xffff0000, v84
	v_lshlrev_b32_e32 v26, 16, v82
	v_and_b32_e32 v27, 0xffff0000, v82
	v_lshlrev_b32_e32 v32, 16, v85
	v_and_b32_e32 v33, 0xffff0000, v85
	v_lshlrev_b32_e32 v28, 16, v83
	v_and_b32_e32 v29, 0xffff0000, v83
	v_pk_mul_f32 v[26:27], v[90:91], v[26:27]
	v_pk_mul_f32 v[32:33], v[96:97], v[32:33]
	v_pk_mul_f32 v[30:31], v[92:93], v[30:31]
	v_pk_mul_f32 v[28:29], v[94:95], v[28:29]
	v_pk_fma_f32 v[22:23], v[22:23], v[70:71], v[26:27]
	v_pk_fma_f32 v[26:27], v[20:21], v[68:69], v[32:33]
	v_pk_fma_f32 v[20:21], v[18:19], v[66:67], v[30:31]
	v_pk_fma_f32 v[24:25], v[24:25], v[72:73], v[28:29]
	v_mov_b32_e32 v28, v23
	v_mov_b32_e32 v29, v21
	v_mov_b32_e32 v18, v22
	v_mov_b32_e32 v19, v20
	v_pk_mul_f32 v[28:29], v[28:29], v[28:29]
	v_mov_b32_e32 v30, v25
	v_mov_b32_e32 v31, v27
	v_pk_fma_f32 v[18:19], v[18:19], v[18:19], v[28:29]
	v_mov_b32_e32 v28, v24
	v_mov_b32_e32 v29, v26
	v_pk_mul_f32 v[30:31], v[30:31], v[30:31]
	v_add_u32_e32 v34, 0x48100, v188
	v_pk_fma_f32 v[28:29], v[28:29], v[28:29], v[30:31]
	v_cvt_pk_bf16_f32 v20, v20, v21
	v_pk_add_f32 v[18:19], v[18:19], v[28:29]
	v_cvt_pk_bf16_f32 v21, v26, v27
	v_add_f32_e32 v18, v18, v19
	v_add_f32_e32 v18, v102, v18
	v_cvt_pk_bf16_f32 v19, v24, v25
	v_cvt_pk_bf16_f32 v18, v22, v23
	global_store_dwordx4 v34, v[18:21], s[96:97]
	s_waitcnt vmcnt(7)
	v_lshlrev_b32_e32 v22, 16, v80
	v_and_b32_e32 v23, 0xffff0000, v80
	v_lshlrev_b32_e32 v18, 16, v78
	v_and_b32_e32 v19, 0xffff0000, v78
	v_lshlrev_b32_e32 v24, 16, v81
	v_and_b32_e32 v25, 0xffff0000, v81
	v_lshlrev_b32_e32 v20, 16, v79
	v_and_b32_e32 v21, 0xffff0000, v79
	v_pk_mul_f32 v[18:19], v[90:91], v[18:19]
	v_pk_mul_f32 v[24:25], v[96:97], v[24:25]
	v_pk_mul_f32 v[22:23], v[92:93], v[22:23]
	v_pk_mul_f32 v[20:21], v[94:95], v[20:21]
	v_pk_fma_f32 v[14:15], v[14:15], v[70:71], v[18:19]
	v_pk_fma_f32 v[18:19], v[12:13], v[68:69], v[24:25]
	v_pk_fma_f32 v[12:13], v[10:11], v[66:67], v[22:23]
	v_pk_fma_f32 v[16:17], v[16:17], v[72:73], v[20:21]
	v_mov_b32_e32 v20, v15
	v_mov_b32_e32 v21, v13
	v_mov_b32_e32 v10, v14
	v_mov_b32_e32 v11, v12
	v_pk_mul_f32 v[20:21], v[20:21], v[20:21]
	v_mov_b32_e32 v22, v17
	v_mov_b32_e32 v23, v19
	v_pk_fma_f32 v[10:11], v[10:11], v[10:11], v[20:21]
	v_mov_b32_e32 v20, v16
	v_mov_b32_e32 v21, v18
	v_pk_mul_f32 v[22:23], v[22:23], v[22:23]
	v_add_u32_e32 v26, 0x50100, v188
	v_pk_fma_f32 v[20:21], v[20:21], v[20:21], v[22:23]
	v_cvt_pk_bf16_f32 v12, v12, v13
	v_pk_add_f32 v[10:11], v[10:11], v[20:21]
	v_cvt_pk_bf16_f32 v13, v18, v19
	v_add_f32_e32 v10, v10, v11
	v_add_f32_e32 v10, v101, v10
	v_cvt_pk_bf16_f32 v11, v16, v17
	v_cvt_pk_bf16_f32 v10, v14, v15
	global_store_dwordx4 v26, v[10:13], s[96:97]
	s_waitcnt vmcnt(7)
	v_lshlrev_b32_e32 v14, 16, v76
	v_and_b32_e32 v15, 0xffff0000, v76
	v_lshlrev_b32_e32 v10, 16, v74
	v_and_b32_e32 v11, 0xffff0000, v74
	v_lshlrev_b32_e32 v16, 16, v77
	v_and_b32_e32 v17, 0xffff0000, v77
	v_lshlrev_b32_e32 v12, 16, v75
	v_and_b32_e32 v13, 0xffff0000, v75
	v_pk_mul_f32 v[10:11], v[90:91], v[10:11]
	v_pk_mul_f32 v[16:17], v[96:97], v[16:17]
	v_pk_mul_f32 v[14:15], v[92:93], v[14:15]
	v_pk_mul_f32 v[12:13], v[94:95], v[12:13]
	v_pk_fma_f32 v[6:7], v[6:7], v[70:71], v[10:11]
	v_pk_fma_f32 v[10:11], v[4:5], v[68:69], v[16:17]
	v_pk_fma_f32 v[4:5], v[2:3], v[66:67], v[14:15]
	v_pk_fma_f32 v[8:9], v[8:9], v[72:73], v[12:13]
	v_mov_b32_e32 v12, v7
	v_mov_b32_e32 v13, v5
	v_mov_b32_e32 v2, v6
	v_mov_b32_e32 v3, v4
	v_pk_mul_f32 v[12:13], v[12:13], v[12:13]
	v_mov_b32_e32 v14, v9
	v_mov_b32_e32 v15, v11
	v_pk_fma_f32 v[2:3], v[2:3], v[2:3], v[12:13]
	v_mov_b32_e32 v12, v8
	v_mov_b32_e32 v13, v10
	v_pk_mul_f32 v[14:15], v[14:15], v[14:15]
	v_add_u32_e32 v18, 0x58100, v188
	v_pk_fma_f32 v[12:13], v[12:13], v[12:13], v[14:15]
	v_cvt_pk_bf16_f32 v4, v4, v5
	v_pk_add_f32 v[2:3], v[2:3], v[12:13]
	v_cvt_pk_bf16_f32 v5, v10, v11
	v_add_f32_e32 v2, v2, v3
	v_add_f32_e32 v2, v100, v2
	v_cvt_pk_bf16_f32 v3, v8, v9
	v_cvt_pk_bf16_f32 v2, v6, v7
	global_store_dwordx4 v18, v[2:5], s[96:97]
	s_cbranch_vccnz .LBB0_1517
	s_andn2_b64 vcc, exec, s[22:23]
	s_cbranch_vccnz .LBB0_1516
	s_barrier
	s_branch .LBB0_1516
